# v8 + attention loop: K/V tile DMA issue moved from behind the QK^T MFMAs into the gaps behind MFMAs 4-7 of that phase
# speedup vs baseline: 1.0172x; 1.0007x over previous
.LBB0_1309:
	s_waitcnt lgkmcnt(7)
	v_mfma_f32_32x32x16_bf16 v[114:129], v[190:193], v[150:153], v[218:233]
	v_add_f32_e32 v98, v82, v83
	v_add_f32_e32 v98, v84, v98
	v_add_f32_e32 v98, v85, v98
	v_add_f32_e32 v98, v86, v98
	v_add_u32_e32 v247, s30, v246
	v_add_f32_e32 v98, v87, v98
	v_cvt_pk_bf16_f32 v158, v82, v83
	v_cvt_pk_bf16_f32 v159, v84, v85
	s_nop 0
	v_add_f32_e32 v82, v88, v98
	s_waitcnt lgkmcnt(6)
	v_mfma_f32_32x32x16_bf16 v[98:113], v[182:185], v[150:153], v[218:233]
	v_add_f32_e32 v82, v89, v82
	v_add_f32_e32 v82, v90, v82
	v_add_f32_e32 v82, v91, v82
	v_cvt_pk_bf16_f32 v160, v86, v87
	v_cvt_pk_bf16_f32 v161, v88, v89
	s_waitcnt lgkmcnt(5)
	v_mfma_f32_32x32x16_bf16 v[114:129], v[186:189], v[146:149], v[114:129]
	v_add_f32_e32 v82, v92, v82
	v_add_f32_e32 v82, v93, v82
	v_add_f32_e32 v82, v94, v82
	v_add_f32_e32 v82, v95, v82
	v_cvt_pk_bf16_f32 v154, v90, v91
	v_cvt_pk_bf16_f32 v155, v92, v93
	s_waitcnt lgkmcnt(4)
	v_mfma_f32_32x32x16_bf16 v[98:113], v[178:181], v[146:149], v[98:113]
	v_add_f32_e32 v82, v96, v82
	v_add_f32_e32 v82, v97, v82
	v_add_f32_e32 v82, v66, v82
	v_add_f32_e32 v86, v67, v82
	v_cvt_pk_bf16_f32 v156, v94, v95
	v_cvt_pk_bf16_f32 v157, v96, v97
	ds_read_b64_tr_b16 v[82:83], v247 offset:49152
	ds_read_b64_tr_b16 v[84:85], v247 offset:49664
	v_lshl_add_u64 v[188:189], v[214:215], 0, s[52:53]
	v_lshl_add_u64 v[92:93], v[188:189], 0, s[70:71]
	s_add_i32 s27, s91, s25
	s_mov_b32 s30, m0
	s_mov_b32 m0, s27
	s_nop 0
	global_load_lds_dwordx4 v[92:93], off
	s_mov_b32 m0, s30
	s_waitcnt lgkmcnt(5)
	v_mfma_f32_32x32x16_bf16 v[114:129], v[174:177], v[142:145], v[114:129]
	v_add_f32_e32 v86, v68, v86
	v_add_f32_e32 v86, v69, v86
	v_add_f32_e32 v86, v70, v86
	v_add_f32_e32 v86, v71, v86
	v_cvt_pk_bf16_f32 v138, v66, v67
	v_cvt_pk_bf16_f32 v139, v68, v69
	ds_read_b64_tr_b16 v[66:67], v247 offset:50176
	ds_read_b64_tr_b16 v[68:69], v247 offset:50688
	v_lshl_add_u64 v[92:93], v[188:189], 0, s[72:73]
	v_lshl_add_u64 v[186:187], v[216:217], 0, s[52:53]
	s_addk_i32 s27, 0x2000
	s_mov_b32 s30, m0
	s_mov_b32 m0, s27
	s_nop 0
	global_load_lds_dwordx4 v[92:93], off
	s_mov_b32 m0, s30
	s_waitcnt lgkmcnt(6)
	v_mfma_f32_32x32x16_bf16 v[98:113], v[170:173], v[142:145], v[98:113]
	v_add_f32_e32 v86, v72, v86
	v_add_f32_e32 v86, v73, v86
	v_add_f32_e32 v86, v74, v86
	v_add_f32_e32 v86, v75, v86
	v_cvt_pk_bf16_f32 v140, v70, v71
	v_cvt_pk_bf16_f32 v141, v72, v73
	ds_read_b64_tr_b16 v[70:71], v247 offset:53248
	ds_read_b64_tr_b16 v[72:73], v247 offset:53760
	v_lshl_add_u64 v[92:93], v[186:187], 0, s[74:75]
	s_add_i32 s27, s29, s24
	s_mov_b32 s30, m0
	s_mov_b32 m0, s27
	s_nop 0
	global_load_lds_dwordx4 v[92:93], off
	s_mov_b32 m0, s30
	s_waitcnt lgkmcnt(7)
	v_mfma_f32_32x32x16_bf16 v[114:129], v[166:169], v[134:137], v[114:129]
	v_add_f32_e32 v86, v76, v86
	v_add_f32_e32 v86, v77, v86
	v_add_f32_e32 v86, v78, v86
	v_add_f32_e32 v86, v79, v86
	v_cvt_pk_bf16_f32 v130, v74, v75
	v_cvt_pk_bf16_f32 v131, v76, v77
	ds_read_b64_tr_b16 v[74:75], v247 offset:54272
	ds_read_b64_tr_b16 v[76:77], v247 offset:54784
	v_lshl_add_u64 v[92:93], v[186:187], 0, s[76:77]
	s_addk_i32 s27, 0x2000
	s_mov_b32 s30, m0
	s_mov_b32 m0, s27
	s_nop 0
	global_load_lds_dwordx4 v[92:93], off
	s_mov_b32 m0, s30
	s_waitcnt lgkmcnt(8)
	v_mfma_f32_32x32x16_bf16 v[98:113], v[162:165], v[134:137], v[98:113]
	v_add_f32_e32 v86, v80, v86
	v_add_f32_e32 v86, v81, v86
	v_add_f32_e32 v86, 0, v86
	v_cvt_pk_bf16_f32 v132, v78, v79
	v_cvt_pk_bf16_f32 v133, v80, v81
	v_max_f32_e32 v78, v115, v115
	v_max_f32_e32 v79, v114, v114
	v_max_f32_e32 v78, v79, v78
	v_max3_f32 v79, v116, v117, v99
	v_max3_f32 v78, v78, v98, v100
	v_max3_f32 v78, v78, v101, v118
	v_max3_f32 v79, v79, v120, v121
	v_max3_f32 v78, v78, v119, v102
	v_max3_f32 v79, v79, v104, v105
	v_max3_f32 v78, v78, v103, v122
	v_max3_f32 v79, v79, v124, v125
	v_max3_f32 v78, v78, v123, v106
	v_max3_f32 v79, v79, v108, v109
	v_max3_f32 v78, v78, v107, v126
	v_max3_f32 v79, v79, v128, v129
	v_max3_f32 v78, v78, v127, v110
	v_max3_f32 v79, v79, v112, v113
	v_max3_f32 v78, v78, v111, v79
	v_mov_b32_e32 v79, v78
	s_nop 1
	v_permlane32_swap_b32_e32 v78, v79
	v_max_f32_e32 v79, v79, v79
	v_max_f32_e32 v78, v78, v78
	v_max_f32_e32 v78, v78, v79
	v_cmp_lt_f32_e32 vcc, s93, v78
	s_cmp_lg_u64 vcc, 0
	v_add_f32_e32 v190, v250, v86
	s_cselect_b64 s[36:37], -1, 0
	s_cbranch_vccnz .LBB0_1317

.LBB0_1312:
	s_add_i32 s27, s29, 0x4000
	s_cmpk_lg_u32 s29, 0x8000
	s_cselect_b32 s27, s27, 0
	v_mfma_f32_32x32x16_bf16 v[82:97], v[70:73], v[150:153], v[218:233]
	v_add_f32_e32 v74, v114, v115
	v_add_f32_e32 v74, v116, v74
	v_add_f32_e32 v74, v117, v74
	v_add_f32_e32 v74, v118, v74
	v_add_u32_e32 v247, s91, v246
	v_add_f32_e32 v74, v119, v74
	v_cvt_pk_bf16_f32 v158, v114, v115
	v_cvt_pk_bf16_f32 v159, v116, v117
	s_nop 0
	v_add_f32_e32 v70, v120, v74
	v_add_f32_e32 v70, v121, v70
	v_add_f32_e32 v70, v122, v70
	v_add_f32_e32 v114, v123, v70
	v_mfma_f32_32x32x16_bf16 v[66:81], v[66:69], v[150:153], v[218:233]
	v_cvt_pk_bf16_f32 v160, v118, v119
	v_cvt_pk_bf16_f32 v161, v120, v121
	v_mfma_f32_32x32x16_bf16 v[82:97], v[182:185], v[146:149], v[82:97]
	v_add_f32_e32 v114, v124, v114
	v_add_f32_e32 v114, v125, v114
	v_add_f32_e32 v114, v126, v114
	v_add_f32_e32 v114, v127, v114
	v_cvt_pk_bf16_f32 v154, v122, v123
	v_cvt_pk_bf16_f32 v155, v124, v125
	v_mfma_f32_32x32x16_bf16 v[66:81], v[174:177], v[146:149], v[66:81]
	v_add_f32_e32 v114, v128, v114
	v_add_f32_e32 v114, v129, v114
	v_add_f32_e32 v114, v98, v114
	v_add_f32_e32 v118, v99, v114
	v_cvt_pk_bf16_f32 v156, v126, v127
	v_cvt_pk_bf16_f32 v157, v128, v129
	ds_read_b64_tr_b16 v[114:115], v247 offset:49152
	ds_read_b64_tr_b16 v[116:117], v247 offset:49664
	s_mov_b64 s[30:31], 0x1dd40000
	v_lshl_add_u64 v[124:125], v[188:189], 0, s[30:31]
	s_add_i32 s36, s29, s25
	s_mov_b32 s30, m0
	s_mov_b32 m0, s36
	s_nop 0
	global_load_lds_dwordx4 v[124:125], off
	s_mov_b32 m0, s30
	v_mfma_f32_32x32x16_bf16 v[82:97], v[178:181], v[142:145], v[82:97]
	v_add_f32_e32 v118, v100, v118
	v_add_f32_e32 v118, v101, v118
	v_add_f32_e32 v118, v102, v118
	v_add_f32_e32 v118, v103, v118
	v_cvt_pk_bf16_f32 v138, v98, v99
	v_cvt_pk_bf16_f32 v139, v100, v101
	ds_read_b64_tr_b16 v[98:99], v247 offset:50176
	ds_read_b64_tr_b16 v[100:101], v247 offset:50688
	s_mov_b64 s[30:31], 0x1dd40080
	v_lshl_add_u64 v[124:125], v[188:189], 0, s[30:31]
	s_add_i32 s30, s36, 0x2000
	s_mov_b32 s31, m0
	s_mov_b32 m0, s30
	s_nop 0
	global_load_lds_dwordx4 v[124:125], off
	s_mov_b32 m0, s31
	v_mfma_f32_32x32x16_bf16 v[66:81], v[166:169], v[142:145], v[66:81]
	v_add_f32_e32 v118, v104, v118
	v_add_f32_e32 v118, v105, v118
	v_add_f32_e32 v118, v106, v118
	v_add_f32_e32 v118, v107, v118
	v_cvt_pk_bf16_f32 v140, v102, v103
	v_cvt_pk_bf16_f32 v141, v104, v105
	ds_read_b64_tr_b16 v[102:103], v247 offset:53248
	ds_read_b64_tr_b16 v[104:105], v247 offset:53760
	s_mov_b64 s[30:31], 0x25cc0000
	v_lshl_add_u64 v[124:125], v[186:187], 0, s[30:31]
	s_add_i32 s36, s27, s24
	s_mov_b32 s30, m0
	s_mov_b32 m0, s36
	s_nop 0
	global_load_lds_dwordx4 v[124:125], off
	s_mov_b32 m0, s30
	v_mfma_f32_32x32x16_bf16 v[82:97], v[170:173], v[134:137], v[82:97]
	v_add_f32_e32 v118, v108, v118
	v_add_f32_e32 v118, v109, v118
	v_add_f32_e32 v118, v110, v118
	v_add_f32_e32 v118, v111, v118
	v_cvt_pk_bf16_f32 v130, v106, v107
	v_cvt_pk_bf16_f32 v131, v108, v109
	ds_read_b64_tr_b16 v[106:107], v247 offset:54272
	ds_read_b64_tr_b16 v[108:109], v247 offset:54784
	s_mov_b64 s[30:31], 0x25cc0080
	v_lshl_add_u64 v[124:125], v[186:187], 0, s[30:31]
	s_add_i32 s30, s36, 0x2000
	s_mov_b32 s31, m0
	s_mov_b32 m0, s30
	s_nop 0
	global_load_lds_dwordx4 v[124:125], off
	s_mov_b32 m0, s31
	v_mfma_f32_32x32x16_bf16 v[66:81], v[162:165], v[134:137], v[66:81]
	v_add_f32_e32 v118, v112, v118
	v_add_f32_e32 v118, v113, v118
	v_add_f32_e32 v118, 0, v118
	v_cvt_pk_bf16_f32 v132, v110, v111
	v_cvt_pk_bf16_f32 v133, v112, v113
	v_max_f32_e32 v110, v83, v83
	v_max_f32_e32 v111, v82, v82
	v_max_f32_e32 v110, v111, v110
	v_max3_f32 v111, v84, v85, v67
	v_max3_f32 v110, v110, v66, v68
	v_max3_f32 v110, v110, v69, v86
	v_max3_f32 v111, v111, v88, v89
	v_max3_f32 v110, v110, v87, v70
	v_max3_f32 v111, v111, v72, v73
	v_max3_f32 v110, v110, v71, v90
	v_max3_f32 v111, v111, v92, v93
	v_max3_f32 v110, v110, v91, v74
	v_max3_f32 v111, v111, v76, v77
	v_max3_f32 v110, v110, v75, v94
	v_max3_f32 v111, v111, v96, v97
	v_max3_f32 v110, v110, v95, v78
	v_max3_f32 v111, v111, v80, v81
	v_max3_f32 v110, v110, v79, v111
	v_mov_b32_e32 v111, v110
	s_nop 1
	v_permlane32_swap_b32_e32 v110, v111
	v_max_f32_e32 v111, v111, v111
	v_max_f32_e32 v110, v110, v110
	v_max_f32_e32 v110, v110, v111
	v_cmp_lt_f32_e32 vcc, s93, v110
	s_cmp_lg_u64 vcc, 0
	v_add_f32_e32 v250, v190, v118
	s_cselect_b64 s[36:37], -1, 0
	s_cbranch_vccnz .LBB0_1320
